# cache policy: partial-sum loads of the context-row norm non-temporal
# baseline (speedup 1.0000x reference)
; __device__ __forceinline__ void norm_phase(const float* xs_lat, const float* xs_ctx, const float* partA, const float* partB, float* xc_wr, int row_begin, int rows, const float* gain, const float* modl, int shoff, int scoff, bf16_t* H, int gw, int NGW, int lane) {
;     ...
;             if (!lat && partA != nullptr) {
;                 const size_t ro = (size_t)(row - ML) * D;
; #pragma unroll
;                 for (int j = 0; j < 4; ++j) { const int ix = 64 * j + lane;
;                     v[u][j] = (((v[u][j] + ((const f32x4*)(partA + ro))[ix]) + ((const f32x4*)(partA + (size_t)MC * D + ro))[ix]) + ((const f32x4*)(partB + ro))[ix]) + ((const f32x4*)(partB + (size_t)MC * D + ro))[ix];
;                     ((f32x4*)(xc_wr + ro))[ix] = v[u][j]; }
;             }
.LBB0_1162:
	s_or_b64 s[4:5], s[10:11], s[42:43]
	s_and_b64 vcc, exec, s[4:5]
	s_cbranch_vccnz .LBB0_1164
	s_lshl_b64 s[4:5], s[34:35], 12
	v_lshl_add_u64 v[68:69], v[42:43], 0, s[4:5]
	v_lshl_add_u64 v[70:71], v[44:45], 0, s[4:5]
	v_lshl_add_u64 v[72:73], v[46:47], 0, s[4:5]
	v_lshl_add_u64 v[74:75], v[48:49], 0, s[4:5]
	v_lshl_add_u64 v[76:77], v[50:51], 0, s[4:5]
	global_load_dwordx4 v[132:135], v[68:69], off nt
	global_load_dwordx4 v[136:139], v[70:71], off nt
	global_load_dwordx4 v[140:143], v[72:73], off nt
	global_load_dwordx4 v[144:147], v[74:75], off nt
	global_load_dwordx4 v[148:151], v[68:69], off offset:1024 nt
	global_load_dwordx4 v[152:155], v[70:71], off offset:1024 nt
	global_load_dwordx4 v[160:163], v[72:73], off offset:1024 nt
	global_load_dwordx4 v[164:167], v[74:75], off offset:1024 nt
	global_load_dwordx4 v[168:171], v[68:69], off offset:2048 nt
	global_load_dwordx4 v[208:211], v[70:71], off offset:2048 nt
	global_load_dwordx4 v[212:215], v[72:73], off offset:2048 nt
	global_load_dwordx4 v[226:229], v[74:75], off offset:2048 nt
	global_load_dwordx4 v[230:233], v[68:69], off offset:3072 nt
	global_load_dwordx4 v[234:237], v[70:71], off offset:3072 nt
	global_load_dwordx4 v[238:241], v[72:73], off offset:3072 nt
	global_load_dwordx4 v[242:245], v[74:75], off offset:3072 nt
	s_waitcnt vmcnt(0)
	v_pk_add_f32 v[20:21], v[20:21], v[132:133]
	v_pk_add_f32 v[22:23], v[22:23], v[134:135]
	v_pk_add_f32 v[20:21], v[20:21], v[136:137]
	v_pk_add_f32 v[22:23], v[22:23], v[138:139]
	v_pk_add_f32 v[20:21], v[20:21], v[140:141]
	v_pk_add_f32 v[22:23], v[22:23], v[142:143]
	v_pk_add_f32 v[20:21], v[20:21], v[144:145]
	v_pk_add_f32 v[22:23], v[22:23], v[146:147]
	global_store_dwordx4 v[76:77], v[20:23], off
	v_pk_add_f32 v[28:29], v[28:29], v[148:149]
	v_pk_add_f32 v[30:31], v[30:31], v[150:151]
	v_pk_add_f32 v[28:29], v[28:29], v[152:153]
	v_pk_add_f32 v[30:31], v[30:31], v[154:155]
	v_pk_add_f32 v[28:29], v[28:29], v[160:161]
	v_pk_add_f32 v[30:31], v[30:31], v[162:163]
	v_pk_add_f32 v[28:29], v[28:29], v[164:165]
	v_pk_add_f32 v[30:31], v[30:31], v[166:167]
	global_store_dwordx4 v[76:77], v[28:31], off offset:1024
	v_pk_add_f32 v[16:17], v[16:17], v[168:169]
	v_pk_add_f32 v[18:19], v[18:19], v[170:171]
	v_pk_add_f32 v[16:17], v[16:17], v[208:209]
	v_pk_add_f32 v[18:19], v[18:19], v[210:211]
	v_pk_add_f32 v[16:17], v[16:17], v[212:213]
	v_pk_add_f32 v[18:19], v[18:19], v[214:215]
	v_pk_add_f32 v[16:17], v[16:17], v[226:227]
	v_pk_add_f32 v[18:19], v[18:19], v[228:229]
	global_store_dwordx4 v[76:77], v[16:19], off offset:2048
	v_pk_add_f32 v[24:25], v[24:25], v[230:231]
	v_pk_add_f32 v[26:27], v[26:27], v[232:233]
	v_pk_add_f32 v[24:25], v[24:25], v[234:235]
	v_pk_add_f32 v[26:27], v[26:27], v[236:237]
	v_pk_add_f32 v[24:25], v[24:25], v[238:239]
	v_pk_add_f32 v[26:27], v[26:27], v[240:241]
	v_pk_add_f32 v[24:25], v[24:25], v[242:243]
	v_pk_add_f32 v[26:27], v[26:27], v[244:245]
	global_store_dwordx4 v[76:77], v[24:27], off offset:3072
